# speedup vs baseline: 1.0038x; 1.0035x over previous
; template <int SHIFT, int NBITS, bool FIRST>
; __device__ __forceinline__ void radix_pass(const unsigned (&uu)[128], int nreg, unsigned* hist, int lane, unsigned& prefix, int& need) {
;     ...
;     for (int g = 0; g < 8; ++g) {
;         if (g * 16 < nreg) {
; #pragma unroll
;             for (int r = g * 16; r < g * 16 + 16; ++r) {
;                 const unsigned u = uu[r];
;                 const bool match = FIRST ? true : ((u >> (SHIFT + NBITS)) == prefix);
;                 if (match) __hip_atomic_fetch_add(hist + ((u >> SHIFT) & (NBINS - 1)), 1u, __ATOMIC_RELAXED, __HIP_MEMORY_SCOPE_WORKGROUP);
;             }
;         }
.LBB0_376:
	v_lshrrev_b32_e32 v131, 21, v113
	v_cmpx_eq_u32_e32 vcc, s55, v131
	v_lshrrev_b32_e32 v131, 8, v113
	v_and_b32_e32 v131, 0x1ffc, v131
	v_add_u32_e32 v131, s97, v131
	ds_add_u32 v131, v176 offset:41984
	s_mov_b64 exec, -1
	v_lshrrev_b32_e32 v131, 21, v112
	v_cmpx_eq_u32_e32 vcc, s55, v131
	v_lshrrev_b32_e32 v131, 8, v112
	v_and_b32_e32 v131, 0x1ffc, v131
	v_add_u32_e32 v131, s97, v131
	ds_add_u32 v131, v176 offset:41984
	s_mov_b64 exec, -1
	v_lshrrev_b32_e32 v131, 21, v111
	v_cmpx_eq_u32_e32 vcc, s55, v131
	v_lshrrev_b32_e32 v131, 8, v111
	v_and_b32_e32 v131, 0x1ffc, v131
	v_add_u32_e32 v131, s97, v131
	ds_add_u32 v131, v176 offset:41984
	s_mov_b64 exec, -1
	v_lshrrev_b32_e32 v131, 21, v110
	v_cmpx_eq_u32_e32 vcc, s55, v131
	v_lshrrev_b32_e32 v131, 8, v110
	v_and_b32_e32 v131, 0x1ffc, v131
	v_add_u32_e32 v131, s97, v131
	ds_add_u32 v131, v176 offset:41984
	s_mov_b64 exec, -1
	v_lshrrev_b32_e32 v131, 21, v109
	v_cmpx_eq_u32_e32 vcc, s55, v131
	v_lshrrev_b32_e32 v131, 8, v109
	v_and_b32_e32 v131, 0x1ffc, v131
	v_add_u32_e32 v131, s97, v131
	ds_add_u32 v131, v176 offset:41984
	s_mov_b64 exec, -1
	v_lshrrev_b32_e32 v131, 21, v108
	v_cmpx_eq_u32_e32 vcc, s55, v131
	v_lshrrev_b32_e32 v131, 8, v108
	v_and_b32_e32 v131, 0x1ffc, v131
	v_add_u32_e32 v131, s97, v131
	ds_add_u32 v131, v176 offset:41984
	s_mov_b64 exec, -1
	v_lshrrev_b32_e32 v131, 21, v107
	v_cmpx_eq_u32_e32 vcc, s55, v131
	v_lshrrev_b32_e32 v131, 8, v107
	v_and_b32_e32 v131, 0x1ffc, v131
	v_add_u32_e32 v131, s97, v131
	ds_add_u32 v131, v176 offset:41984
	s_mov_b64 exec, -1
	v_lshrrev_b32_e32 v131, 21, v106
	v_cmpx_eq_u32_e32 vcc, s55, v131
	v_lshrrev_b32_e32 v131, 8, v106
	v_and_b32_e32 v131, 0x1ffc, v131
	v_add_u32_e32 v131, s97, v131
	ds_add_u32 v131, v176 offset:41984
	s_mov_b64 exec, -1
	v_lshrrev_b32_e32 v131, 21, v105
	v_cmpx_eq_u32_e32 vcc, s55, v131
	v_lshrrev_b32_e32 v131, 8, v105
	v_and_b32_e32 v131, 0x1ffc, v131
	v_add_u32_e32 v131, s97, v131
	ds_add_u32 v131, v176 offset:41984
	s_mov_b64 exec, -1
	v_lshrrev_b32_e32 v131, 21, v104
	v_cmpx_eq_u32_e32 vcc, s55, v131
	v_lshrrev_b32_e32 v131, 8, v104
	v_and_b32_e32 v131, 0x1ffc, v131
	v_add_u32_e32 v131, s97, v131
	ds_add_u32 v131, v176 offset:41984
	s_mov_b64 exec, -1
	v_lshrrev_b32_e32 v131, 21, v103
	v_cmpx_eq_u32_e32 vcc, s55, v131
	v_lshrrev_b32_e32 v131, 8, v103
	v_and_b32_e32 v131, 0x1ffc, v131
	v_add_u32_e32 v131, s97, v131
	ds_add_u32 v131, v176 offset:41984
	s_mov_b64 exec, -1
	v_lshrrev_b32_e32 v131, 21, v102
	v_cmpx_eq_u32_e32 vcc, s55, v131
	v_lshrrev_b32_e32 v131, 8, v102
	v_and_b32_e32 v131, 0x1ffc, v131
	v_add_u32_e32 v131, s97, v131
	ds_add_u32 v131, v176 offset:41984
	s_mov_b64 exec, -1
	v_lshrrev_b32_e32 v131, 21, v101
	v_cmpx_eq_u32_e32 vcc, s55, v131
	v_lshrrev_b32_e32 v131, 8, v101
	v_and_b32_e32 v131, 0x1ffc, v131
	v_add_u32_e32 v131, s97, v131
	ds_add_u32 v131, v176 offset:41984
	s_mov_b64 exec, -1
	v_lshrrev_b32_e32 v131, 21, v100
	v_cmpx_eq_u32_e32 vcc, s55, v131
	v_lshrrev_b32_e32 v131, 8, v100
	v_and_b32_e32 v131, 0x1ffc, v131
	v_add_u32_e32 v131, s97, v131
	ds_add_u32 v131, v176 offset:41984
	s_mov_b64 exec, -1
	v_lshrrev_b32_e32 v131, 21, v99
	v_cmpx_eq_u32_e32 vcc, s55, v131
	v_lshrrev_b32_e32 v131, 8, v99
	v_and_b32_e32 v131, 0x1ffc, v131
	v_add_u32_e32 v131, s97, v131
	ds_add_u32 v131, v176 offset:41984
	s_mov_b64 exec, -1
	v_lshrrev_b32_e32 v131, 21, v97
	v_cmpx_eq_u32_e32 vcc, s55, v131
	v_lshrrev_b32_e32 v131, 8, v97
	v_and_b32_e32 v131, 0x1ffc, v131
	v_add_u32_e32 v131, s97, v131
	ds_add_u32 v131, v176 offset:41984
	s_mov_b64 exec, -1
	v_cndmask_b32_e64 v131, 0, 1, s[28:29]
	v_cmp_ne_u32_e64 s[26:27], 1, v131
	s_andn2_b64 vcc, exec, s[28:29]
	s_cbranch_vccnz .LBB0_344
.LBB0_409:
	v_lshrrev_b32_e32 v131, 21, v98
	v_cmpx_eq_u32_e32 vcc, s55, v131
	v_lshrrev_b32_e32 v131, 8, v98
	v_and_b32_e32 v131, 0x1ffc, v131
	v_add_u32_e32 v131, s97, v131
	ds_add_u32 v131, v176 offset:41984
	s_mov_b64 exec, -1
	v_lshrrev_b32_e32 v131, 21, v96
	v_cmpx_eq_u32_e32 vcc, s55, v131
	v_lshrrev_b32_e32 v131, 8, v96
	v_and_b32_e32 v131, 0x1ffc, v131
	v_add_u32_e32 v131, s97, v131
	ds_add_u32 v131, v176 offset:41984
	s_mov_b64 exec, -1
	v_lshrrev_b32_e32 v131, 21, v95
	v_cmpx_eq_u32_e32 vcc, s55, v131
	v_lshrrev_b32_e32 v131, 8, v95
	v_and_b32_e32 v131, 0x1ffc, v131
	v_add_u32_e32 v131, s97, v131
	ds_add_u32 v131, v176 offset:41984
	s_mov_b64 exec, -1
	v_lshrrev_b32_e32 v131, 21, v94
	v_cmpx_eq_u32_e32 vcc, s55, v131
	v_lshrrev_b32_e32 v131, 8, v94
	v_and_b32_e32 v131, 0x1ffc, v131
	v_add_u32_e32 v131, s97, v131
	ds_add_u32 v131, v176 offset:41984
	s_mov_b64 exec, -1
	v_lshrrev_b32_e32 v131, 21, v93
	v_cmpx_eq_u32_e32 vcc, s55, v131
	v_lshrrev_b32_e32 v131, 8, v93
	v_and_b32_e32 v131, 0x1ffc, v131
	v_add_u32_e32 v131, s97, v131
	ds_add_u32 v131, v176 offset:41984
	s_mov_b64 exec, -1
	v_lshrrev_b32_e32 v131, 21, v92
	v_cmpx_eq_u32_e32 vcc, s55, v131
	v_lshrrev_b32_e32 v131, 8, v92
	v_and_b32_e32 v131, 0x1ffc, v131
	v_add_u32_e32 v131, s97, v131
	ds_add_u32 v131, v176 offset:41984
	s_mov_b64 exec, -1
	v_lshrrev_b32_e32 v131, 21, v91
	v_cmpx_eq_u32_e32 vcc, s55, v131
	v_lshrrev_b32_e32 v131, 8, v91
	v_and_b32_e32 v131, 0x1ffc, v131
	v_add_u32_e32 v131, s97, v131
	ds_add_u32 v131, v176 offset:41984
	s_mov_b64 exec, -1
	v_lshrrev_b32_e32 v131, 21, v90
	v_cmpx_eq_u32_e32 vcc, s55, v131
	v_lshrrev_b32_e32 v131, 8, v90
	v_and_b32_e32 v131, 0x1ffc, v131
	v_add_u32_e32 v131, s97, v131
	ds_add_u32 v131, v176 offset:41984
	s_mov_b64 exec, -1
	v_lshrrev_b32_e32 v131, 21, v89
	v_cmpx_eq_u32_e32 vcc, s55, v131
	v_lshrrev_b32_e32 v131, 8, v89
	v_and_b32_e32 v131, 0x1ffc, v131
	v_add_u32_e32 v131, s97, v131
; template <int SHIFT, int NBITS, bool FIRST>
; __device__ __forceinline__ void radix_pass(const unsigned (&uu)[128], int nreg, unsigned* hist, int lane, unsigned& prefix, int& need) {
;     ...
;     for (int g = 0; g < 8; ++g) {
;         if (g * 16 < nreg) {
; #pragma unroll
;             for (int r = g * 16; r < g * 16 + 16; ++r) {
;                 const unsigned u = uu[r];
;                 const bool match = FIRST ? true : ((u >> (SHIFT + NBITS)) == prefix);
;                 if (match) __hip_atomic_fetch_add(hist + ((u >> SHIFT) & (NBINS - 1)), 1u, __ATOMIC_RELAXED, __HIP_MEMORY_SCOPE_WORKGROUP);
;             }
;         }
	ds_add_u32 v131, v176 offset:41984
	s_mov_b64 exec, -1
	v_lshrrev_b32_e32 v131, 21, v88
	v_cmpx_eq_u32_e32 vcc, s55, v131
	v_lshrrev_b32_e32 v131, 8, v88
	v_and_b32_e32 v131, 0x1ffc, v131
	v_add_u32_e32 v131, s97, v131
	ds_add_u32 v131, v176 offset:41984
	s_mov_b64 exec, -1
	v_lshrrev_b32_e32 v131, 21, v87
	v_cmpx_eq_u32_e32 vcc, s55, v131
	v_lshrrev_b32_e32 v131, 8, v87
	v_and_b32_e32 v131, 0x1ffc, v131
	v_add_u32_e32 v131, s97, v131
	ds_add_u32 v131, v176 offset:41984
	s_mov_b64 exec, -1
	v_lshrrev_b32_e32 v131, 21, v86
	v_cmpx_eq_u32_e32 vcc, s55, v131
	v_lshrrev_b32_e32 v131, 8, v86
	v_and_b32_e32 v131, 0x1ffc, v131
	v_add_u32_e32 v131, s97, v131
	ds_add_u32 v131, v176 offset:41984
	s_mov_b64 exec, -1
	v_lshrrev_b32_e32 v131, 21, v85
	v_cmpx_eq_u32_e32 vcc, s55, v131
	v_lshrrev_b32_e32 v131, 8, v85
	v_and_b32_e32 v131, 0x1ffc, v131
	v_add_u32_e32 v131, s97, v131
	ds_add_u32 v131, v176 offset:41984
	s_mov_b64 exec, -1
	v_lshrrev_b32_e32 v131, 21, v84
	v_cmpx_eq_u32_e32 vcc, s55, v131
	v_lshrrev_b32_e32 v131, 8, v84
	v_and_b32_e32 v131, 0x1ffc, v131
	v_add_u32_e32 v131, s97, v131
	ds_add_u32 v131, v176 offset:41984
	s_mov_b64 exec, -1
	v_lshrrev_b32_e32 v131, 21, v83
	v_cmpx_eq_u32_e32 vcc, s55, v131
	v_lshrrev_b32_e32 v131, 8, v83
	v_and_b32_e32 v131, 0x1ffc, v131
	v_add_u32_e32 v131, s97, v131
	ds_add_u32 v131, v176 offset:41984
	s_mov_b64 exec, -1
	v_lshrrev_b32_e32 v131, 21, v79
	v_cmpx_eq_u32_e32 vcc, s55, v131
	v_lshrrev_b32_e32 v131, 8, v79
	v_and_b32_e32 v131, 0x1ffc, v131
	v_add_u32_e32 v131, s97, v131
	ds_add_u32 v131, v176 offset:41984
	s_mov_b64 exec, -1
	v_cndmask_b32_e64 v131, 0, 1, s[30:31]
	v_cmp_ne_u32_e64 s[28:29], 1, v131
	s_andn2_b64 vcc, exec, s[30:31]
	s_cbranch_vccnz .LBB0_345
.LBB0_442:
	v_lshrrev_b32_e32 v131, 21, v82
	v_cmpx_eq_u32_e32 vcc, s55, v131
	v_lshrrev_b32_e32 v131, 8, v82
	v_and_b32_e32 v131, 0x1ffc, v131
	v_add_u32_e32 v131, s97, v131
	ds_add_u32 v131, v176 offset:41984
	s_mov_b64 exec, -1
	v_lshrrev_b32_e32 v131, 21, v81
	v_cmpx_eq_u32_e32 vcc, s55, v131
	v_lshrrev_b32_e32 v131, 8, v81
	v_and_b32_e32 v131, 0x1ffc, v131
	v_add_u32_e32 v131, s97, v131
	ds_add_u32 v131, v176 offset:41984
	s_mov_b64 exec, -1
	v_lshrrev_b32_e32 v131, 21, v80
	v_cmpx_eq_u32_e32 vcc, s55, v131
	v_lshrrev_b32_e32 v131, 8, v80
	v_and_b32_e32 v131, 0x1ffc, v131
	v_add_u32_e32 v131, s97, v131
	ds_add_u32 v131, v176 offset:41984
	s_mov_b64 exec, -1
	v_lshrrev_b32_e32 v131, 21, v78
	v_cmpx_eq_u32_e32 vcc, s55, v131
	v_lshrrev_b32_e32 v131, 8, v78
	v_and_b32_e32 v131, 0x1ffc, v131
	v_add_u32_e32 v131, s97, v131
	ds_add_u32 v131, v176 offset:41984
	s_mov_b64 exec, -1
	v_lshrrev_b32_e32 v131, 21, v77
	v_cmpx_eq_u32_e32 vcc, s55, v131
	v_lshrrev_b32_e32 v131, 8, v77
	v_and_b32_e32 v131, 0x1ffc, v131
	v_add_u32_e32 v131, s97, v131
	ds_add_u32 v131, v176 offset:41984
	s_mov_b64 exec, -1
	v_lshrrev_b32_e32 v131, 21, v76
	v_cmpx_eq_u32_e32 vcc, s55, v131
	v_lshrrev_b32_e32 v131, 8, v76
	v_and_b32_e32 v131, 0x1ffc, v131
	v_add_u32_e32 v131, s97, v131
	ds_add_u32 v131, v176 offset:41984
	s_mov_b64 exec, -1
	v_lshrrev_b32_e32 v131, 21, v75
	v_cmpx_eq_u32_e32 vcc, s55, v131
	v_lshrrev_b32_e32 v131, 8, v75
	v_and_b32_e32 v131, 0x1ffc, v131
	v_add_u32_e32 v131, s97, v131
	ds_add_u32 v131, v176 offset:41984
	s_mov_b64 exec, -1
	v_lshrrev_b32_e32 v131, 21, v74
	v_cmpx_eq_u32_e32 vcc, s55, v131
	v_lshrrev_b32_e32 v131, 8, v74
	v_and_b32_e32 v131, 0x1ffc, v131
	v_add_u32_e32 v131, s97, v131
	ds_add_u32 v131, v176 offset:41984
	s_mov_b64 exec, -1
	v_lshrrev_b32_e32 v131, 21, v73
	v_cmpx_eq_u32_e32 vcc, s55, v131
	v_lshrrev_b32_e32 v131, 8, v73
	v_and_b32_e32 v131, 0x1ffc, v131
	v_add_u32_e32 v131, s97, v131
	ds_add_u32 v131, v176 offset:41984
	s_mov_b64 exec, -1
	v_lshrrev_b32_e32 v131, 21, v72
	v_cmpx_eq_u32_e32 vcc, s55, v131
	v_lshrrev_b32_e32 v131, 8, v72
	v_and_b32_e32 v131, 0x1ffc, v131
	v_add_u32_e32 v131, s97, v131
	ds_add_u32 v131, v176 offset:41984
	s_mov_b64 exec, -1
	v_lshrrev_b32_e32 v131, 21, v71
	v_cmpx_eq_u32_e32 vcc, s55, v131
	v_lshrrev_b32_e32 v131, 8, v71
	v_and_b32_e32 v131, 0x1ffc, v131
	v_add_u32_e32 v131, s97, v131
	ds_add_u32 v131, v176 offset:41984
	s_mov_b64 exec, -1
	v_lshrrev_b32_e32 v131, 21, v70
	v_cmpx_eq_u32_e32 vcc, s55, v131
	v_lshrrev_b32_e32 v131, 8, v70
	v_and_b32_e32 v131, 0x1ffc, v131
	v_add_u32_e32 v131, s97, v131
	ds_add_u32 v131, v176 offset:41984
	s_mov_b64 exec, -1
	v_lshrrev_b32_e32 v131, 21, v69
	v_cmpx_eq_u32_e32 vcc, s55, v131
	v_lshrrev_b32_e32 v131, 8, v69
	v_and_b32_e32 v131, 0x1ffc, v131
	v_add_u32_e32 v131, s97, v131
	ds_add_u32 v131, v176 offset:41984
	s_mov_b64 exec, -1
	v_lshrrev_b32_e32 v131, 21, v68
	v_cmpx_eq_u32_e32 vcc, s55, v131
	v_lshrrev_b32_e32 v131, 8, v68
	v_and_b32_e32 v131, 0x1ffc, v131
	v_add_u32_e32 v131, s97, v131
	ds_add_u32 v131, v176 offset:41984
	s_mov_b64 exec, -1
	v_lshrrev_b32_e32 v131, 21, v67
	v_cmpx_eq_u32_e32 vcc, s55, v131
	v_lshrrev_b32_e32 v131, 8, v67
	v_and_b32_e32 v131, 0x1ffc, v131
	v_add_u32_e32 v131, s97, v131
	ds_add_u32 v131, v176 offset:41984
	s_mov_b64 exec, -1
	v_lshrrev_b32_e32 v131, 21, v65
	v_cmpx_eq_u32_e32 vcc, s55, v131
	v_lshrrev_b32_e32 v131, 8, v65
	v_and_b32_e32 v131, 0x1ffc, v131
	v_add_u32_e32 v131, s97, v131
	ds_add_u32 v131, v176 offset:41984
	s_mov_b64 exec, -1
	v_cndmask_b32_e64 v131, 0, 1, s[34:35]
	v_cmp_ne_u32_e64 s[30:31], 1, v131
	s_andn2_b64 vcc, exec, s[34:35]
	s_cbranch_vccnz .LBB0_346
; template <int SHIFT, int NBITS, bool FIRST>
; __device__ __forceinline__ void radix_pass(const unsigned (&uu)[128], int nreg, unsigned* hist, int lane, unsigned& prefix, int& need) {
;     ...
;     for (int g = 0; g < 8; ++g) {
;         if (g * 16 < nreg) {
; #pragma unroll
;             for (int r = g * 16; r < g * 16 + 16; ++r) {
;                 const unsigned u = uu[r];
;                 const bool match = FIRST ? true : ((u >> (SHIFT + NBITS)) == prefix);
;                 if (match) __hip_atomic_fetch_add(hist + ((u >> SHIFT) & (NBINS - 1)), 1u, __ATOMIC_RELAXED, __HIP_MEMORY_SCOPE_WORKGROUP);
;             }
;         }
.LBB0_475:
	v_lshrrev_b32_e32 v131, 21, v66
	v_cmpx_eq_u32_e32 vcc, s55, v131
	v_lshrrev_b32_e32 v131, 8, v66
	v_and_b32_e32 v131, 0x1ffc, v131
	v_add_u32_e32 v131, s97, v131
	ds_add_u32 v131, v176 offset:41984
	s_mov_b64 exec, -1
	v_lshrrev_b32_e32 v131, 21, v64
	v_cmpx_eq_u32_e32 vcc, s55, v131
	v_lshrrev_b32_e32 v131, 8, v64
	v_and_b32_e32 v131, 0x1ffc, v131
	v_add_u32_e32 v131, s97, v131
	ds_add_u32 v131, v176 offset:41984
	s_mov_b64 exec, -1
	v_lshrrev_b32_e32 v131, 21, v63
	v_cmpx_eq_u32_e32 vcc, s55, v131
	v_lshrrev_b32_e32 v131, 8, v63
	v_and_b32_e32 v131, 0x1ffc, v131
	v_add_u32_e32 v131, s97, v131
	ds_add_u32 v131, v176 offset:41984
	s_mov_b64 exec, -1
	v_lshrrev_b32_e32 v131, 21, v62
	v_cmpx_eq_u32_e32 vcc, s55, v131
	v_lshrrev_b32_e32 v131, 8, v62
	v_and_b32_e32 v131, 0x1ffc, v131
	v_add_u32_e32 v131, s97, v131
	ds_add_u32 v131, v176 offset:41984
	s_mov_b64 exec, -1
	v_lshrrev_b32_e32 v131, 21, v61
	v_cmpx_eq_u32_e32 vcc, s55, v131
	v_lshrrev_b32_e32 v131, 8, v61
	v_and_b32_e32 v131, 0x1ffc, v131
	v_add_u32_e32 v131, s97, v131
	ds_add_u32 v131, v176 offset:41984
	s_mov_b64 exec, -1
	v_lshrrev_b32_e32 v131, 21, v60
	v_cmpx_eq_u32_e32 vcc, s55, v131
	v_lshrrev_b32_e32 v131, 8, v60
	v_and_b32_e32 v131, 0x1ffc, v131
	v_add_u32_e32 v131, s97, v131
	ds_add_u32 v131, v176 offset:41984
	s_mov_b64 exec, -1
	v_lshrrev_b32_e32 v131, 21, v59
	v_cmpx_eq_u32_e32 vcc, s55, v131
	v_lshrrev_b32_e32 v131, 8, v59
	v_and_b32_e32 v131, 0x1ffc, v131
	v_add_u32_e32 v131, s97, v131
	ds_add_u32 v131, v176 offset:41984
	s_mov_b64 exec, -1
	v_lshrrev_b32_e32 v131, 21, v58
	v_cmpx_eq_u32_e32 vcc, s55, v131
	v_lshrrev_b32_e32 v131, 8, v58
	v_and_b32_e32 v131, 0x1ffc, v131
	v_add_u32_e32 v131, s97, v131
	ds_add_u32 v131, v176 offset:41984
	s_mov_b64 exec, -1
	v_lshrrev_b32_e32 v131, 21, v57
	v_cmpx_eq_u32_e32 vcc, s55, v131
	v_lshrrev_b32_e32 v131, 8, v57
	v_and_b32_e32 v131, 0x1ffc, v131
	v_add_u32_e32 v131, s97, v131
	ds_add_u32 v131, v176 offset:41984
	s_mov_b64 exec, -1
	v_lshrrev_b32_e32 v131, 21, v56
	v_cmpx_eq_u32_e32 vcc, s55, v131
	v_lshrrev_b32_e32 v131, 8, v56
	v_and_b32_e32 v131, 0x1ffc, v131
	v_add_u32_e32 v131, s97, v131
	ds_add_u32 v131, v176 offset:41984
	s_mov_b64 exec, -1
	v_lshrrev_b32_e32 v131, 21, v55
	v_cmpx_eq_u32_e32 vcc, s55, v131
	v_lshrrev_b32_e32 v131, 8, v55
	v_and_b32_e32 v131, 0x1ffc, v131
	v_add_u32_e32 v131, s97, v131
	ds_add_u32 v131, v176 offset:41984
	s_mov_b64 exec, -1
	v_lshrrev_b32_e32 v131, 21, v54
	v_cmpx_eq_u32_e32 vcc, s55, v131
	v_lshrrev_b32_e32 v131, 8, v54
	v_and_b32_e32 v131, 0x1ffc, v131
	v_add_u32_e32 v131, s97, v131
	ds_add_u32 v131, v176 offset:41984
	s_mov_b64 exec, -1
	v_lshrrev_b32_e32 v131, 21, v53
	v_cmpx_eq_u32_e32 vcc, s55, v131
	v_lshrrev_b32_e32 v131, 8, v53
	v_and_b32_e32 v131, 0x1ffc, v131
	v_add_u32_e32 v131, s97, v131
	ds_add_u32 v131, v176 offset:41984
	s_mov_b64 exec, -1
	v_lshrrev_b32_e32 v131, 21, v52
	v_cmpx_eq_u32_e32 vcc, s55, v131
	v_lshrrev_b32_e32 v131, 8, v52
	v_and_b32_e32 v131, 0x1ffc, v131
	v_add_u32_e32 v131, s97, v131
	ds_add_u32 v131, v176 offset:41984
	s_mov_b64 exec, -1
	v_lshrrev_b32_e32 v131, 21, v51
	v_cmpx_eq_u32_e32 vcc, s55, v131
	v_lshrrev_b32_e32 v131, 8, v51
	v_and_b32_e32 v131, 0x1ffc, v131
	v_add_u32_e32 v131, s97, v131
	ds_add_u32 v131, v176 offset:41984
	s_mov_b64 exec, -1
	v_lshrrev_b32_e32 v131, 21, v47
	v_cmpx_eq_u32_e32 vcc, s55, v131
	v_lshrrev_b32_e32 v131, 8, v47
	v_and_b32_e32 v131, 0x1ffc, v131
	v_add_u32_e32 v131, s97, v131
	ds_add_u32 v131, v176 offset:41984
	s_mov_b64 exec, -1
	v_cndmask_b32_e64 v131, 0, 1, s[36:37]
	v_cmp_ne_u32_e64 s[34:35], 1, v131
	s_andn2_b64 vcc, exec, s[36:37]
	s_cbranch_vccnz .LBB0_347
.LBB0_508:
	v_lshrrev_b32_e32 v131, 21, v50
	v_cmpx_eq_u32_e32 vcc, s55, v131
	v_lshrrev_b32_e32 v131, 8, v50
	v_and_b32_e32 v131, 0x1ffc, v131
	v_add_u32_e32 v131, s97, v131
	ds_add_u32 v131, v176 offset:41984
	s_mov_b64 exec, -1
	v_lshrrev_b32_e32 v131, 21, v49
	v_cmpx_eq_u32_e32 vcc, s55, v131
	v_lshrrev_b32_e32 v131, 8, v49
	v_and_b32_e32 v131, 0x1ffc, v131
	v_add_u32_e32 v131, s97, v131
	ds_add_u32 v131, v176 offset:41984
	s_mov_b64 exec, -1
	v_lshrrev_b32_e32 v131, 21, v48
	v_cmpx_eq_u32_e32 vcc, s55, v131
	v_lshrrev_b32_e32 v131, 8, v48
	v_and_b32_e32 v131, 0x1ffc, v131
	v_add_u32_e32 v131, s97, v131
	ds_add_u32 v131, v176 offset:41984
	s_mov_b64 exec, -1
	v_lshrrev_b32_e32 v131, 21, v46
	v_cmpx_eq_u32_e32 vcc, s55, v131
	v_lshrrev_b32_e32 v131, 8, v46
	v_and_b32_e32 v131, 0x1ffc, v131
	v_add_u32_e32 v131, s97, v131
	ds_add_u32 v131, v176 offset:41984
	s_mov_b64 exec, -1
	v_lshrrev_b32_e32 v131, 21, v45
	v_cmpx_eq_u32_e32 vcc, s55, v131
	v_lshrrev_b32_e32 v131, 8, v45
	v_and_b32_e32 v131, 0x1ffc, v131
	v_add_u32_e32 v131, s97, v131
	ds_add_u32 v131, v176 offset:41984
	s_mov_b64 exec, -1
	v_lshrrev_b32_e32 v131, 21, v44
	v_cmpx_eq_u32_e32 vcc, s55, v131
	v_lshrrev_b32_e32 v131, 8, v44
	v_and_b32_e32 v131, 0x1ffc, v131
	v_add_u32_e32 v131, s97, v131
	ds_add_u32 v131, v176 offset:41984
	s_mov_b64 exec, -1
	v_lshrrev_b32_e32 v131, 21, v43
	v_cmpx_eq_u32_e32 vcc, s55, v131
	v_lshrrev_b32_e32 v131, 8, v43
	v_and_b32_e32 v131, 0x1ffc, v131
	v_add_u32_e32 v131, s97, v131
	ds_add_u32 v131, v176 offset:41984
	s_mov_b64 exec, -1
	v_lshrrev_b32_e32 v131, 21, v42
	v_cmpx_eq_u32_e32 vcc, s55, v131
	v_lshrrev_b32_e32 v131, 8, v42
	v_and_b32_e32 v131, 0x1ffc, v131
	v_add_u32_e32 v131, s97, v131
	ds_add_u32 v131, v176 offset:41984
	s_mov_b64 exec, -1
	v_lshrrev_b32_e32 v131, 21, v41
	v_cmpx_eq_u32_e32 vcc, s55, v131
	v_lshrrev_b32_e32 v131, 8, v41
	v_and_b32_e32 v131, 0x1ffc, v131
	v_add_u32_e32 v131, s97, v131
	ds_add_u32 v131, v176 offset:41984
; template <int SHIFT, int NBITS, bool FIRST>
; __device__ __forceinline__ void radix_pass(const unsigned (&uu)[128], int nreg, unsigned* hist, int lane, unsigned& prefix, int& need) {
;     ...
;     for (int g = 0; g < 8; ++g) {
;         if (g * 16 < nreg) {
; #pragma unroll
;             for (int r = g * 16; r < g * 16 + 16; ++r) {
;                 const unsigned u = uu[r];
;                 const bool match = FIRST ? true : ((u >> (SHIFT + NBITS)) == prefix);
;                 if (match) __hip_atomic_fetch_add(hist + ((u >> SHIFT) & (NBINS - 1)), 1u, __ATOMIC_RELAXED, __HIP_MEMORY_SCOPE_WORKGROUP);
;             }
;         }
	s_mov_b64 exec, -1
	v_lshrrev_b32_e32 v131, 21, v40
	v_cmpx_eq_u32_e32 vcc, s55, v131
	v_lshrrev_b32_e32 v131, 8, v40
	v_and_b32_e32 v131, 0x1ffc, v131
	v_add_u32_e32 v131, s97, v131
	ds_add_u32 v131, v176 offset:41984
	s_mov_b64 exec, -1
	v_lshrrev_b32_e32 v131, 21, v39
	v_cmpx_eq_u32_e32 vcc, s55, v131
	v_lshrrev_b32_e32 v131, 8, v39
	v_and_b32_e32 v131, 0x1ffc, v131
	v_add_u32_e32 v131, s97, v131
	ds_add_u32 v131, v176 offset:41984
	s_mov_b64 exec, -1
	v_lshrrev_b32_e32 v131, 21, v38
	v_cmpx_eq_u32_e32 vcc, s55, v131
	v_lshrrev_b32_e32 v131, 8, v38
	v_and_b32_e32 v131, 0x1ffc, v131
	v_add_u32_e32 v131, s97, v131
	ds_add_u32 v131, v176 offset:41984
	s_mov_b64 exec, -1
	v_lshrrev_b32_e32 v131, 21, v37
	v_cmpx_eq_u32_e32 vcc, s55, v131
	v_lshrrev_b32_e32 v131, 8, v37
	v_and_b32_e32 v131, 0x1ffc, v131
	v_add_u32_e32 v131, s97, v131
	ds_add_u32 v131, v176 offset:41984
	s_mov_b64 exec, -1
	v_lshrrev_b32_e32 v131, 21, v36
	v_cmpx_eq_u32_e32 vcc, s55, v131
	v_lshrrev_b32_e32 v131, 8, v36
	v_and_b32_e32 v131, 0x1ffc, v131
	v_add_u32_e32 v131, s97, v131
	ds_add_u32 v131, v176 offset:41984
	s_mov_b64 exec, -1
	v_lshrrev_b32_e32 v131, 21, v35
	v_cmpx_eq_u32_e32 vcc, s55, v131
	v_lshrrev_b32_e32 v131, 8, v35
	v_and_b32_e32 v131, 0x1ffc, v131
	v_add_u32_e32 v131, s97, v131
	ds_add_u32 v131, v176 offset:41984
	s_mov_b64 exec, -1
	v_lshrrev_b32_e32 v131, 21, v33
	v_cmpx_eq_u32_e32 vcc, s55, v131
	v_lshrrev_b32_e32 v131, 8, v33
	v_and_b32_e32 v131, 0x1ffc, v131
	v_add_u32_e32 v131, s97, v131
	ds_add_u32 v131, v176 offset:41984
	s_mov_b64 exec, -1
	v_cndmask_b32_e64 v131, 0, 1, s[38:39]
	v_cmp_ne_u32_e64 s[36:37], 1, v131
	s_andn2_b64 vcc, exec, s[38:39]
	s_cbranch_vccnz .LBB0_348
.LBB0_541:
	v_lshrrev_b32_e32 v131, 21, v34
	v_cmpx_eq_u32_e32 vcc, s55, v131
	v_lshrrev_b32_e32 v131, 8, v34
	v_and_b32_e32 v131, 0x1ffc, v131
	v_add_u32_e32 v131, s97, v131
	ds_add_u32 v131, v176 offset:41984
	s_mov_b64 exec, -1
	v_lshrrev_b32_e32 v131, 21, v32
	v_cmpx_eq_u32_e32 vcc, s55, v131
	v_lshrrev_b32_e32 v131, 8, v32
	v_and_b32_e32 v131, 0x1ffc, v131
	v_add_u32_e32 v131, s97, v131
	ds_add_u32 v131, v176 offset:41984
	s_mov_b64 exec, -1
	v_lshrrev_b32_e32 v131, 21, v31
	v_cmpx_eq_u32_e32 vcc, s55, v131
	v_lshrrev_b32_e32 v131, 8, v31
	v_and_b32_e32 v131, 0x1ffc, v131
	v_add_u32_e32 v131, s97, v131
	ds_add_u32 v131, v176 offset:41984
	s_mov_b64 exec, -1
	v_lshrrev_b32_e32 v131, 21, v30
	v_cmpx_eq_u32_e32 vcc, s55, v131
	v_lshrrev_b32_e32 v131, 8, v30
	v_and_b32_e32 v131, 0x1ffc, v131
	v_add_u32_e32 v131, s97, v131
	ds_add_u32 v131, v176 offset:41984
	s_mov_b64 exec, -1
	v_lshrrev_b32_e32 v131, 21, v29
	v_cmpx_eq_u32_e32 vcc, s55, v131
	v_lshrrev_b32_e32 v131, 8, v29
	v_and_b32_e32 v131, 0x1ffc, v131
	v_add_u32_e32 v131, s97, v131
	ds_add_u32 v131, v176 offset:41984
	s_mov_b64 exec, -1
	v_lshrrev_b32_e32 v131, 21, v28
	v_cmpx_eq_u32_e32 vcc, s55, v131
	v_lshrrev_b32_e32 v131, 8, v28
	v_and_b32_e32 v131, 0x1ffc, v131
	v_add_u32_e32 v131, s97, v131
	ds_add_u32 v131, v176 offset:41984
	s_mov_b64 exec, -1
	v_lshrrev_b32_e32 v131, 21, v27
	v_cmpx_eq_u32_e32 vcc, s55, v131
	v_lshrrev_b32_e32 v131, 8, v27
	v_and_b32_e32 v131, 0x1ffc, v131
	v_add_u32_e32 v131, s97, v131
	ds_add_u32 v131, v176 offset:41984
	s_mov_b64 exec, -1
	v_lshrrev_b32_e32 v131, 21, v26
	v_cmpx_eq_u32_e32 vcc, s55, v131
	v_lshrrev_b32_e32 v131, 8, v26
	v_and_b32_e32 v131, 0x1ffc, v131
	v_add_u32_e32 v131, s97, v131
	ds_add_u32 v131, v176 offset:41984
	s_mov_b64 exec, -1
	v_lshrrev_b32_e32 v131, 21, v25
	v_cmpx_eq_u32_e32 vcc, s55, v131
	v_lshrrev_b32_e32 v131, 8, v25
	v_and_b32_e32 v131, 0x1ffc, v131
	v_add_u32_e32 v131, s97, v131
	ds_add_u32 v131, v176 offset:41984
	s_mov_b64 exec, -1
	v_lshrrev_b32_e32 v131, 21, v24
	v_cmpx_eq_u32_e32 vcc, s55, v131
	v_lshrrev_b32_e32 v131, 8, v24
	v_and_b32_e32 v131, 0x1ffc, v131
	v_add_u32_e32 v131, s97, v131
	ds_add_u32 v131, v176 offset:41984
	s_mov_b64 exec, -1
	v_lshrrev_b32_e32 v131, 21, v23
	v_cmpx_eq_u32_e32 vcc, s55, v131
	v_lshrrev_b32_e32 v131, 8, v23
	v_and_b32_e32 v131, 0x1ffc, v131
	v_add_u32_e32 v131, s97, v131
	ds_add_u32 v131, v176 offset:41984
	s_mov_b64 exec, -1
	v_lshrrev_b32_e32 v131, 21, v22
	v_cmpx_eq_u32_e32 vcc, s55, v131
	v_lshrrev_b32_e32 v131, 8, v22
	v_and_b32_e32 v131, 0x1ffc, v131
	v_add_u32_e32 v131, s97, v131
	ds_add_u32 v131, v176 offset:41984
	s_mov_b64 exec, -1
	v_lshrrev_b32_e32 v131, 21, v21
	v_cmpx_eq_u32_e32 vcc, s55, v131
	v_lshrrev_b32_e32 v131, 8, v21
	v_and_b32_e32 v131, 0x1ffc, v131
	v_add_u32_e32 v131, s97, v131
	ds_add_u32 v131, v176 offset:41984
	s_mov_b64 exec, -1
	v_lshrrev_b32_e32 v131, 21, v20
	v_cmpx_eq_u32_e32 vcc, s55, v131
	v_lshrrev_b32_e32 v131, 8, v20
	v_and_b32_e32 v131, 0x1ffc, v131
	v_add_u32_e32 v131, s97, v131
	ds_add_u32 v131, v176 offset:41984
	s_mov_b64 exec, -1
	v_lshrrev_b32_e32 v131, 21, v19
	v_cmpx_eq_u32_e32 vcc, s55, v131
	v_lshrrev_b32_e32 v131, 8, v19
	v_and_b32_e32 v131, 0x1ffc, v131
	v_add_u32_e32 v131, s97, v131
	ds_add_u32 v131, v176 offset:41984
	s_mov_b64 exec, -1
	v_lshrrev_b32_e32 v131, 21, v15
	v_cmpx_eq_u32_e32 vcc, s55, v131
	v_lshrrev_b32_e32 v131, 8, v15
	v_and_b32_e32 v131, 0x1ffc, v131
	v_add_u32_e32 v131, s97, v131
	ds_add_u32 v131, v176 offset:41984
	s_mov_b64 exec, -1
	v_cndmask_b32_e64 v131, 0, 1, s[62:63]
	v_cmp_ne_u32_e64 s[38:39], 1, v131
	s_andn2_b64 vcc, exec, s[62:63]
	s_cbranch_vccnz .LBB0_607
; template <int SHIFT, int NBITS, bool FIRST>
; __device__ __forceinline__ void radix_pass(const unsigned (&uu)[128], int nreg, unsigned* hist, int lane, unsigned& prefix, int& need) {
;     ...
;     for (int g = 0; g < 8; ++g) {
;         if (g * 16 < nreg) {
; #pragma unroll
;             for (int r = g * 16; r < g * 16 + 16; ++r) {
;                 const unsigned u = uu[r];
;                 const bool match = FIRST ? true : ((u >> (SHIFT + NBITS)) == prefix);
;                 if (match) __hip_atomic_fetch_add(hist + ((u >> SHIFT) & (NBINS - 1)), 1u, __ATOMIC_RELAXED, __HIP_MEMORY_SCOPE_WORKGROUP);
;             }
;         }
.LBB0_574:
	v_lshrrev_b32_e32 v131, 21, v18
	v_cmpx_eq_u32_e32 vcc, s55, v131
	v_lshrrev_b32_e32 v131, 8, v18
	v_and_b32_e32 v131, 0x1ffc, v131
	v_add_u32_e32 v131, s97, v131
	ds_add_u32 v131, v176 offset:41984
	s_mov_b64 exec, -1
	v_lshrrev_b32_e32 v131, 21, v17
	v_cmpx_eq_u32_e32 vcc, s55, v131
	v_lshrrev_b32_e32 v131, 8, v17
	v_and_b32_e32 v131, 0x1ffc, v131
	v_add_u32_e32 v131, s97, v131
	ds_add_u32 v131, v176 offset:41984
	s_mov_b64 exec, -1
	v_lshrrev_b32_e32 v131, 21, v16
	v_cmpx_eq_u32_e32 vcc, s55, v131
	v_lshrrev_b32_e32 v131, 8, v16
	v_and_b32_e32 v131, 0x1ffc, v131
	v_add_u32_e32 v131, s97, v131
	ds_add_u32 v131, v176 offset:41984
	s_mov_b64 exec, -1
	v_lshrrev_b32_e32 v131, 21, v14
	v_cmpx_eq_u32_e32 vcc, s55, v131
	v_lshrrev_b32_e32 v131, 8, v14
	v_and_b32_e32 v131, 0x1ffc, v131
	v_add_u32_e32 v131, s97, v131
	ds_add_u32 v131, v176 offset:41984
	s_mov_b64 exec, -1
	v_lshrrev_b32_e32 v131, 21, v13
	v_cmpx_eq_u32_e32 vcc, s55, v131
	v_lshrrev_b32_e32 v131, 8, v13
	v_and_b32_e32 v131, 0x1ffc, v131
	v_add_u32_e32 v131, s97, v131
	ds_add_u32 v131, v176 offset:41984
	s_mov_b64 exec, -1
	v_lshrrev_b32_e32 v131, 21, v12
	v_cmpx_eq_u32_e32 vcc, s55, v131
	v_lshrrev_b32_e32 v131, 8, v12
	v_and_b32_e32 v131, 0x1ffc, v131
	v_add_u32_e32 v131, s97, v131
	ds_add_u32 v131, v176 offset:41984
	s_mov_b64 exec, -1
	v_lshrrev_b32_e32 v131, 21, v11
	v_cmpx_eq_u32_e32 vcc, s55, v131
	v_lshrrev_b32_e32 v131, 8, v11
	v_and_b32_e32 v131, 0x1ffc, v131
	v_add_u32_e32 v131, s97, v131
	ds_add_u32 v131, v176 offset:41984
	s_mov_b64 exec, -1
	v_lshrrev_b32_e32 v131, 21, v10
	v_cmpx_eq_u32_e32 vcc, s55, v131
	v_lshrrev_b32_e32 v131, 8, v10
	v_and_b32_e32 v131, 0x1ffc, v131
	v_add_u32_e32 v131, s97, v131
	ds_add_u32 v131, v176 offset:41984
	s_mov_b64 exec, -1
	v_lshrrev_b32_e32 v131, 21, v9
	v_cmpx_eq_u32_e32 vcc, s55, v131
	v_lshrrev_b32_e32 v131, 8, v9
	v_and_b32_e32 v131, 0x1ffc, v131
	v_add_u32_e32 v131, s97, v131
	ds_add_u32 v131, v176 offset:41984
	s_mov_b64 exec, -1
	v_lshrrev_b32_e32 v131, 21, v8
	v_cmpx_eq_u32_e32 vcc, s55, v131
	v_lshrrev_b32_e32 v131, 8, v8
	v_and_b32_e32 v131, 0x1ffc, v131
	v_add_u32_e32 v131, s97, v131
	ds_add_u32 v131, v176 offset:41984
	s_mov_b64 exec, -1
	v_lshrrev_b32_e32 v131, 21, v7
	v_cmpx_eq_u32_e32 vcc, s55, v131
	v_lshrrev_b32_e32 v131, 8, v7
	v_and_b32_e32 v131, 0x1ffc, v131
	v_add_u32_e32 v131, s97, v131
	ds_add_u32 v131, v176 offset:41984
	s_mov_b64 exec, -1
	v_lshrrev_b32_e32 v131, 21, v6
	v_cmpx_eq_u32_e32 vcc, s55, v131
	v_lshrrev_b32_e32 v131, 8, v6
	v_and_b32_e32 v131, 0x1ffc, v131
	v_add_u32_e32 v131, s97, v131
	ds_add_u32 v131, v176 offset:41984
	s_mov_b64 exec, -1
	v_lshrrev_b32_e32 v131, 21, v5
	v_cmpx_eq_u32_e32 vcc, s55, v131
	v_lshrrev_b32_e32 v131, 8, v5
	v_and_b32_e32 v131, 0x1ffc, v131
	v_add_u32_e32 v131, s97, v131
	ds_add_u32 v131, v176 offset:41984
	s_mov_b64 exec, -1
	v_lshrrev_b32_e32 v131, 21, v4
	v_cmpx_eq_u32_e32 vcc, s55, v131
	v_lshrrev_b32_e32 v131, 8, v4
	v_and_b32_e32 v131, 0x1ffc, v131
	v_add_u32_e32 v131, s97, v131
	ds_add_u32 v131, v176 offset:41984
	s_mov_b64 exec, -1
	v_lshrrev_b32_e32 v131, 21, v3
	v_cmpx_eq_u32_e32 vcc, s55, v131
	v_lshrrev_b32_e32 v131, 8, v3
	v_and_b32_e32 v131, 0x1ffc, v131
	v_add_u32_e32 v131, s97, v131
	ds_add_u32 v131, v176 offset:41984
	s_mov_b64 exec, -1
	v_lshrrev_b32_e32 v131, 21, v2
	v_cmpx_eq_u32_e32 vcc, s55, v131
	v_lshrrev_b32_e32 v131, 8, v2
	v_and_b32_e32 v131, 0x1ffc, v131
	v_add_u32_e32 v131, s97, v131
	ds_add_u32 v131, v176 offset:41984
	s_mov_b64 exec, -1
; #define WAVE_LDS_SYNC() do { __builtin_amdgcn_fence(__ATOMIC_RELEASE, "workgroup"); __builtin_amdgcn_wave_barrier(); __builtin_amdgcn_fence(__ATOMIC_ACQUIRE, "workgroup"); } while (0)
; template <int SHIFT, int NBITS, bool FIRST>
; __device__ __forceinline__ void radix_pass(const unsigned (&uu)[128], int nreg, unsigned* hist, int lane, unsigned& prefix, int& need) {
;     ...
;     for (int i = 0; i < NBINS / 256; ++i) *(u32x4*)(hist + (i * 64 + lane) * 4) = (u32x4){0u, 0u, 0u, 0u};
;     WAVE_LDS_SYNC();
; #pragma unroll
;     for (int g = 0; g < 8; ++g) {
;         if (g * 16 < nreg) {
; #pragma unroll
;             for (int r = g * 16; r < g * 16 + 16; ++r) {
;                 const unsigned u = uu[r];
;                 const bool match = FIRST ? true : ((u >> (SHIFT + NBITS)) == prefix);
;                 if (match) __hip_atomic_fetch_add(hist + ((u >> SHIFT) & (NBINS - 1)), 1u, __ATOMIC_RELAXED, __HIP_MEMORY_SCOPE_WORKGROUP);
;             }
;     ...
;     int T = 0;
;     {
;         const unsigned* hb = hist + (63 - lane) * BPL;
; #pragma unroll
;         for (int i = 0; i < BPL / 4; ++i) { const u32x4 c = *(const u32x4*)(hb + i * 4); T += (int)(c.x + c.y + c.z + c.w); }
;     }
;     const int P = wave_prefix_incl(T);
;     const unsigned long long m1 = __ballot(P >= need);
;     const int lo = __builtin_ctzll(m1);
;     const int above_blk = __builtin_amdgcn_readlane(P - T, lo);
;     const int base = (63 - lo) * BPL;
;     const int c2 = (lane < BPL) ? (int)hist[base + BPL - 1 - (lane < BPL ? lane : 0)] : 0;
;     const int P2 = wave_prefix_incl(c2);
;     const unsigned long long m2 = __ballot((lane < BPL) && (above_blk + P2 >= need));
;     const int j = __builtin_ctzll(m2);
;     const int above = above_blk + __builtin_amdgcn_readlane(P2 - c2, j);
;     prefix = (prefix << NBITS) | (unsigned)(base + BPL - 1 - j);
;     need -= above;
.LBB0_607:
	s_waitcnt lgkmcnt(0)
	ds_read_b128 v[132:135], v130 offset:50048
	ds_read_b128 v[136:139], v130 offset:50064
	ds_read_b128 v[140:143], v130 offset:50080
	ds_read_b128 v[144:147], v130 offset:50096
	s_add_i32 s59, s59, s61
	s_sub_i32 s59, 0x100, s59
	s_waitcnt lgkmcnt(3)
	v_add_u32_e32 v131, v133, v132
	v_add3_u32 v131, v131, v134, v135
	s_waitcnt lgkmcnt(2)
	v_add3_u32 v131, v131, v137, v136
	v_add3_u32 v131, v131, v138, v139
	ds_read_b128 v[132:135], v130 offset:50112
	ds_read_b128 v[136:139], v130 offset:50128
	s_waitcnt lgkmcnt(3)
	v_add3_u32 v131, v131, v141, v140
	v_add3_u32 v131, v131, v142, v143
	s_waitcnt lgkmcnt(2)
	v_add3_u32 v131, v131, v145, v144
	v_add3_u32 v131, v131, v146, v147
	ds_read_b128 v[140:143], v130 offset:50144
	s_waitcnt lgkmcnt(2)
	v_add3_u32 v131, v131, v133, v132
	v_add3_u32 v134, v131, v134, v135
	ds_read_b128 v[130:133], v130 offset:50160
	s_waitcnt lgkmcnt(2)
	v_add3_u32 v134, v134, v137, v136
	v_add3_u32 v134, v134, v138, v139
	s_waitcnt lgkmcnt(1)
	v_add3_u32 v134, v134, v141, v140
	v_add3_u32 v134, v134, v142, v143
	s_waitcnt lgkmcnt(0)
	v_add3_u32 v130, v134, v131, v130
	v_add3_u32 v131, v130, v132, v133
	v_mov_b32_e32 v130, 0
	s_nop 0
	v_add_u32_dpp v132, v131, v131 row_shr:1 row_mask:0xf bank_mask:0xf bound_ctrl:1
	s_nop 1
	v_add_u32_dpp v132, v132, v132 row_shr:2 row_mask:0xf bank_mask:0xf bound_ctrl:1
	s_nop 1
	v_add_u32_dpp v132, v132, v132 row_shr:4 row_mask:0xf bank_mask:0xf bound_ctrl:1
	s_nop 1
	v_add_u32_dpp v132, v132, v132 row_shr:8 row_mask:0xf bank_mask:0xf bound_ctrl:1
	s_nop 1
	v_add_u32_dpp v132, v132, v132 row_bcast:15 row_mask:0xa bank_mask:0xf
	s_nop 1
	v_add_u32_dpp v132, v132, v132 row_bcast:31 row_mask:0xc bank_mask:0xf
	v_cmp_le_i32_e32 vcc, s59, v132
	s_ff1_i32_b64 s4, vcc
	v_sub_u32_e32 v131, v132, v131
	s_nop 0
	v_readlane_b32 s61, v131, s4
	s_lshl_b32 s4, s4, 5
	s_xor_b32 s41, s4, 0x7e0
	s_and_saveexec_b64 s[42:43], s[22:23]
	v_sub_u32_e32 v130, s41, v1
	v_lshl_add_u32 v130, v130, 2, s97
	ds_read_b32 v130, v130 offset:42108
	s_or_b64 exec, exec, s[42:43]
	s_waitcnt lgkmcnt(0)
	v_add_u32_dpp v131, v130, v130 row_shr:1 row_mask:0xf bank_mask:0xf bound_ctrl:1
	s_mov_b32 s42, s40
	s_mov_b32 s43, s40
	v_add_u32_dpp v131, v131, v131 row_shr:2 row_mask:0xf bank_mask:0xf bound_ctrl:1
	s_nop 1
	v_add_u32_dpp v131, v131, v131 row_shr:4 row_mask:0xf bank_mask:0xf bound_ctrl:1
	s_nop 1
	v_add_u32_dpp v131, v131, v131 row_shr:8 row_mask:0xf bank_mask:0xf bound_ctrl:1
	s_nop 1
	v_add_u32_dpp v131, v131, v131 row_bcast:15 row_mask:0xa bank_mask:0xf
	s_nop 1
	v_add_u32_dpp v131, v131, v131 row_bcast:31 row_mask:0xc bank_mask:0xf
	v_add_u32_e32 v132, s61, v131
	v_cmp_le_i32_e32 vcc, s59, v132
	s_and_b64 s[4:5], s[22:23], vcc
	v_cndmask_b32_e64 v132, 0, 1, s[4:5]
	v_cmp_ne_u32_e32 vcc, 0, v132
	s_ff1_i32_b64 s4, vcc
	v_sub_u32_e32 v130, v131, v130
	s_or_b32 s22, s41, 31
	v_readlane_b32 s62, v130, s4
	s_mov_b32 s41, s40
	v_mov_b64_e32 v[132:133], s[42:43]
	s_lshl_b32 s5, s55, 11
	s_sub_i32 s4, s22, s4
	v_mov_b64_e32 v[130:131], s[40:41]
	s_or_b32 s55, s4, s5
	ds_write_b128 v129, v[130:133] offset:41984
	ds_write_b128 v129, v[130:133] offset:43008
	ds_write_b128 v129, v[130:133] offset:44032
	ds_write_b128 v129, v[130:133] offset:45056
	v_lshrrev_b32_e32 v129, 10, v0
	v_cmp_eq_u32_e32 vcc, s55, v129
	s_waitcnt lgkmcnt(0)
	s_and_saveexec_b64 s[22:23], vcc
	v_and_b32_e32 v129, 0x3ff, v0
	v_lshl_add_u32 v129, v129, 2, s97
	ds_add_u32 v129, v176 offset:41984
	s_or_b64 exec, exec, s[22:23]
	v_lshrrev_b32_e32 v129, 10, v128
	v_cmpx_eq_u32_e32 vcc, s55, v129
	v_and_b32_e32 v129, 0x3ff, v128
	v_lshl_add_u32 v129, v129, 2, s97
	ds_add_u32 v129, v176 offset:41984
	s_mov_b64 exec, -1
	v_lshrrev_b32_e32 v129, 10, v127
	v_cmpx_eq_u32_e32 vcc, s55, v129
	v_and_b32_e32 v129, 0x3ff, v127
	v_lshl_add_u32 v129, v129, 2, s97
	ds_add_u32 v129, v176 offset:41984
	s_mov_b64 exec, -1
	v_lshrrev_b32_e32 v129, 10, v126
	v_cmpx_eq_u32_e32 vcc, s55, v129
	v_and_b32_e32 v129, 0x3ff, v126
	v_lshl_add_u32 v129, v129, 2, s97
	ds_add_u32 v129, v176 offset:41984
	s_mov_b64 exec, -1
	v_lshrrev_b32_e32 v129, 10, v125
	v_cmpx_eq_u32_e32 vcc, s55, v129
	v_and_b32_e32 v129, 0x3ff, v125
	v_lshl_add_u32 v129, v129, 2, s97
	ds_add_u32 v129, v176 offset:41984
	s_mov_b64 exec, -1
	v_lshrrev_b32_e32 v129, 10, v124
	v_cmpx_eq_u32_e32 vcc, s55, v129
	v_and_b32_e32 v129, 0x3ff, v124
	v_lshl_add_u32 v129, v129, 2, s97
	ds_add_u32 v129, v176 offset:41984
	s_mov_b64 exec, -1
	v_lshrrev_b32_e32 v129, 10, v123
	v_cmpx_eq_u32_e32 vcc, s55, v129
	v_and_b32_e32 v129, 0x3ff, v123
	v_lshl_add_u32 v129, v129, 2, s97
	ds_add_u32 v129, v176 offset:41984
	s_mov_b64 exec, -1
	v_lshrrev_b32_e32 v129, 10, v122
	v_cmpx_eq_u32_e32 vcc, s55, v129
	v_and_b32_e32 v129, 0x3ff, v122
	v_lshl_add_u32 v129, v129, 2, s97
	ds_add_u32 v129, v176 offset:41984
	s_mov_b64 exec, -1
	v_lshrrev_b32_e32 v129, 10, v121
	v_cmpx_eq_u32_e32 vcc, s55, v129
	v_and_b32_e32 v129, 0x3ff, v121
	v_lshl_add_u32 v129, v129, 2, s97
	ds_add_u32 v129, v176 offset:41984
	s_mov_b64 exec, -1
	v_lshrrev_b32_e32 v129, 10, v120
	v_cmpx_eq_u32_e32 vcc, s55, v129
	v_and_b32_e32 v129, 0x3ff, v120
	v_lshl_add_u32 v129, v129, 2, s97
	ds_add_u32 v129, v176 offset:41984
	s_mov_b64 exec, -1
	v_lshrrev_b32_e32 v129, 10, v119
	v_cmpx_eq_u32_e32 vcc, s55, v129
	v_and_b32_e32 v129, 0x3ff, v119
	v_lshl_add_u32 v129, v129, 2, s97
	ds_add_u32 v129, v176 offset:41984
	s_mov_b64 exec, -1
	v_lshrrev_b32_e32 v129, 10, v118
	v_cmpx_eq_u32_e32 vcc, s55, v129
	v_and_b32_e32 v129, 0x3ff, v118
	v_lshl_add_u32 v129, v129, 2, s97
	ds_add_u32 v129, v176 offset:41984
	s_mov_b64 exec, -1
	v_lshrrev_b32_e32 v129, 10, v117
	v_cmpx_eq_u32_e32 vcc, s55, v129
	v_and_b32_e32 v129, 0x3ff, v117
	v_lshl_add_u32 v129, v129, 2, s97
	ds_add_u32 v129, v176 offset:41984
	s_mov_b64 exec, -1
	v_lshrrev_b32_e32 v129, 10, v116
	v_cmpx_eq_u32_e32 vcc, s55, v129
	v_and_b32_e32 v129, 0x3ff, v116
	v_lshl_add_u32 v129, v129, 2, s97
	ds_add_u32 v129, v176 offset:41984
	s_mov_b64 exec, -1
	v_lshrrev_b32_e32 v129, 10, v115
	v_cmpx_eq_u32_e32 vcc, s55, v129
	v_and_b32_e32 v129, 0x3ff, v115
	v_lshl_add_u32 v129, v129, 2, s97
	ds_add_u32 v129, v176 offset:41984
	s_mov_b64 exec, -1
	v_lshrrev_b32_e32 v129, 10, v114
	v_cmp_eq_u32_e32 vcc, s55, v129
	s_and_saveexec_b64 s[22:23], vcc
	s_cbranch_execnz .LBB0_647
	s_or_b64 exec, exec, s[22:23]
	s_and_b64 vcc, exec, s[24:25]
	s_cbranch_vccz .LBB0_648

; template <int SHIFT, int NBITS, bool FIRST>
; __device__ __forceinline__ void radix_pass(const unsigned (&uu)[128], int nreg, unsigned* hist, int lane, unsigned& prefix, int& need) {
;     ...
;     for (int g = 0; g < 8; ++g) {
;         if (g * 16 < nreg) {
; #pragma unroll
;             for (int r = g * 16; r < g * 16 + 16; ++r) {
;                 const unsigned u = uu[r];
;                 const bool match = FIRST ? true : ((u >> (SHIFT + NBITS)) == prefix);
;                 if (match) __hip_atomic_fetch_add(hist + ((u >> SHIFT) & (NBINS - 1)), 1u, __ATOMIC_RELAXED, __HIP_MEMORY_SCOPE_WORKGROUP);
;             }
.LBB0_648:
	v_lshrrev_b32_e32 v129, 10, v113
	v_cmpx_eq_u32_e32 vcc, s55, v129
	v_and_b32_e32 v129, 0x3ff, v113
	v_lshl_add_u32 v129, v129, 2, s97
	ds_add_u32 v129, v176 offset:41984
	s_mov_b64 exec, -1
	v_lshrrev_b32_e32 v129, 10, v112
	v_cmpx_eq_u32_e32 vcc, s55, v129
	v_and_b32_e32 v129, 0x3ff, v112
	v_lshl_add_u32 v129, v129, 2, s97
	ds_add_u32 v129, v176 offset:41984
	s_mov_b64 exec, -1
	v_lshrrev_b32_e32 v129, 10, v111
	v_cmpx_eq_u32_e32 vcc, s55, v129
	v_and_b32_e32 v129, 0x3ff, v111
	v_lshl_add_u32 v129, v129, 2, s97
	ds_add_u32 v129, v176 offset:41984
	s_mov_b64 exec, -1
	v_lshrrev_b32_e32 v129, 10, v110
	v_cmpx_eq_u32_e32 vcc, s55, v129
	v_and_b32_e32 v129, 0x3ff, v110
	v_lshl_add_u32 v129, v129, 2, s97
	ds_add_u32 v129, v176 offset:41984
	s_mov_b64 exec, -1
	v_lshrrev_b32_e32 v129, 10, v109
	v_cmpx_eq_u32_e32 vcc, s55, v129
	v_and_b32_e32 v129, 0x3ff, v109
	v_lshl_add_u32 v129, v129, 2, s97
	ds_add_u32 v129, v176 offset:41984
	s_mov_b64 exec, -1
	v_lshrrev_b32_e32 v129, 10, v108
	v_cmpx_eq_u32_e32 vcc, s55, v129
	v_and_b32_e32 v129, 0x3ff, v108
	v_lshl_add_u32 v129, v129, 2, s97
	ds_add_u32 v129, v176 offset:41984
	s_mov_b64 exec, -1
	v_lshrrev_b32_e32 v129, 10, v107
	v_cmpx_eq_u32_e32 vcc, s55, v129
	v_and_b32_e32 v129, 0x3ff, v107
	v_lshl_add_u32 v129, v129, 2, s97
	ds_add_u32 v129, v176 offset:41984
	s_mov_b64 exec, -1
	v_lshrrev_b32_e32 v129, 10, v106
	v_cmpx_eq_u32_e32 vcc, s55, v129
	v_and_b32_e32 v129, 0x3ff, v106
	v_lshl_add_u32 v129, v129, 2, s97
	ds_add_u32 v129, v176 offset:41984
	s_mov_b64 exec, -1
	v_lshrrev_b32_e32 v129, 10, v105
	v_cmpx_eq_u32_e32 vcc, s55, v129
	v_and_b32_e32 v129, 0x3ff, v105
	v_lshl_add_u32 v129, v129, 2, s97
	ds_add_u32 v129, v176 offset:41984
	s_mov_b64 exec, -1
	v_lshrrev_b32_e32 v129, 10, v104
	v_cmpx_eq_u32_e32 vcc, s55, v129
	v_and_b32_e32 v129, 0x3ff, v104
	v_lshl_add_u32 v129, v129, 2, s97
	ds_add_u32 v129, v176 offset:41984
	s_mov_b64 exec, -1
	v_lshrrev_b32_e32 v129, 10, v103
	v_cmpx_eq_u32_e32 vcc, s55, v129
	v_and_b32_e32 v129, 0x3ff, v103
	v_lshl_add_u32 v129, v129, 2, s97
	ds_add_u32 v129, v176 offset:41984
	s_mov_b64 exec, -1
	v_lshrrev_b32_e32 v129, 10, v102
	v_cmpx_eq_u32_e32 vcc, s55, v129
	v_and_b32_e32 v129, 0x3ff, v102
	v_lshl_add_u32 v129, v129, 2, s97
	ds_add_u32 v129, v176 offset:41984
	s_mov_b64 exec, -1
	v_lshrrev_b32_e32 v129, 10, v101
	v_cmpx_eq_u32_e32 vcc, s55, v129
	v_and_b32_e32 v129, 0x3ff, v101
	v_lshl_add_u32 v129, v129, 2, s97
	ds_add_u32 v129, v176 offset:41984
	s_mov_b64 exec, -1
	v_lshrrev_b32_e32 v129, 10, v100
	v_cmpx_eq_u32_e32 vcc, s55, v129
	v_and_b32_e32 v129, 0x3ff, v100
	v_lshl_add_u32 v129, v129, 2, s97
	ds_add_u32 v129, v176 offset:41984
	s_mov_b64 exec, -1
	v_lshrrev_b32_e32 v129, 10, v99
	v_cmpx_eq_u32_e32 vcc, s55, v129
	v_and_b32_e32 v129, 0x3ff, v99
	v_lshl_add_u32 v129, v129, 2, s97
	ds_add_u32 v129, v176 offset:41984
	s_mov_b64 exec, -1
	v_lshrrev_b32_e32 v129, 10, v97
	v_cmpx_eq_u32_e32 vcc, s55, v129
	v_and_b32_e32 v129, 0x3ff, v97
	v_lshl_add_u32 v129, v129, 2, s97
	ds_add_u32 v129, v176 offset:41984
	s_mov_b64 exec, -1
	s_and_b64 vcc, exec, s[26:27]
	s_cbranch_vccnz .LBB0_642
.LBB0_681:
	v_lshrrev_b32_e32 v129, 10, v98
	v_cmpx_eq_u32_e32 vcc, s55, v129
	v_and_b32_e32 v129, 0x3ff, v98
	v_lshl_add_u32 v129, v129, 2, s97
	ds_add_u32 v129, v176 offset:41984
	s_mov_b64 exec, -1
	v_lshrrev_b32_e32 v129, 10, v96
	v_cmpx_eq_u32_e32 vcc, s55, v129
	v_and_b32_e32 v129, 0x3ff, v96
	v_lshl_add_u32 v129, v129, 2, s97
	ds_add_u32 v129, v176 offset:41984
	s_mov_b64 exec, -1
	v_lshrrev_b32_e32 v129, 10, v95
	v_cmpx_eq_u32_e32 vcc, s55, v129
	v_and_b32_e32 v129, 0x3ff, v95
	v_lshl_add_u32 v129, v129, 2, s97
	ds_add_u32 v129, v176 offset:41984
	s_mov_b64 exec, -1
	v_lshrrev_b32_e32 v129, 10, v94
	v_cmpx_eq_u32_e32 vcc, s55, v129
	v_and_b32_e32 v129, 0x3ff, v94
	v_lshl_add_u32 v129, v129, 2, s97
	ds_add_u32 v129, v176 offset:41984
	s_mov_b64 exec, -1
	v_lshrrev_b32_e32 v129, 10, v93
	v_cmpx_eq_u32_e32 vcc, s55, v129
	v_and_b32_e32 v129, 0x3ff, v93
	v_lshl_add_u32 v129, v129, 2, s97
	ds_add_u32 v129, v176 offset:41984
	s_mov_b64 exec, -1
	v_lshrrev_b32_e32 v129, 10, v92
	v_cmpx_eq_u32_e32 vcc, s55, v129
	v_and_b32_e32 v129, 0x3ff, v92
	v_lshl_add_u32 v129, v129, 2, s97
	ds_add_u32 v129, v176 offset:41984
	s_mov_b64 exec, -1
	v_lshrrev_b32_e32 v129, 10, v91
	v_cmpx_eq_u32_e32 vcc, s55, v129
	v_and_b32_e32 v129, 0x3ff, v91
	v_lshl_add_u32 v129, v129, 2, s97
	ds_add_u32 v129, v176 offset:41984
	s_mov_b64 exec, -1
	v_lshrrev_b32_e32 v129, 10, v90
	v_cmpx_eq_u32_e32 vcc, s55, v129
	v_and_b32_e32 v129, 0x3ff, v90
	v_lshl_add_u32 v129, v129, 2, s97
	ds_add_u32 v129, v176 offset:41984
	s_mov_b64 exec, -1
	v_lshrrev_b32_e32 v129, 10, v89
	v_cmpx_eq_u32_e32 vcc, s55, v129
	v_and_b32_e32 v129, 0x3ff, v89
	v_lshl_add_u32 v129, v129, 2, s97
	ds_add_u32 v129, v176 offset:41984
	s_mov_b64 exec, -1
	v_lshrrev_b32_e32 v129, 10, v88
	v_cmpx_eq_u32_e32 vcc, s55, v129
	v_and_b32_e32 v129, 0x3ff, v88
	v_lshl_add_u32 v129, v129, 2, s97
	ds_add_u32 v129, v176 offset:41984
	s_mov_b64 exec, -1
	v_lshrrev_b32_e32 v129, 10, v87
	v_cmpx_eq_u32_e32 vcc, s55, v129
	v_and_b32_e32 v129, 0x3ff, v87
	v_lshl_add_u32 v129, v129, 2, s97
	ds_add_u32 v129, v176 offset:41984
	s_mov_b64 exec, -1
	v_lshrrev_b32_e32 v129, 10, v86
	v_cmpx_eq_u32_e32 vcc, s55, v129
	v_and_b32_e32 v129, 0x3ff, v86
	v_lshl_add_u32 v129, v129, 2, s97
	ds_add_u32 v129, v176 offset:41984
	s_mov_b64 exec, -1
	v_lshrrev_b32_e32 v129, 10, v85
	v_cmpx_eq_u32_e32 vcc, s55, v129
	v_and_b32_e32 v129, 0x3ff, v85
	v_lshl_add_u32 v129, v129, 2, s97
	ds_add_u32 v129, v176 offset:41984
	s_mov_b64 exec, -1
	v_lshrrev_b32_e32 v129, 10, v84
	v_cmpx_eq_u32_e32 vcc, s55, v129
	v_and_b32_e32 v129, 0x3ff, v84
	v_lshl_add_u32 v129, v129, 2, s97
	ds_add_u32 v129, v176 offset:41984
	s_mov_b64 exec, -1
	v_lshrrev_b32_e32 v129, 10, v83
	v_cmpx_eq_u32_e32 vcc, s55, v129
	v_and_b32_e32 v129, 0x3ff, v83
	v_lshl_add_u32 v129, v129, 2, s97
	ds_add_u32 v129, v176 offset:41984
	s_mov_b64 exec, -1
	v_lshrrev_b32_e32 v129, 10, v79
	v_cmpx_eq_u32_e32 vcc, s55, v129
	v_and_b32_e32 v129, 0x3ff, v79
	v_lshl_add_u32 v129, v129, 2, s97
	ds_add_u32 v129, v176 offset:41984
	s_mov_b64 exec, -1
	s_and_b64 vcc, exec, s[28:29]
	s_cbranch_vccnz .LBB0_643
; template <int SHIFT, int NBITS, bool FIRST>
; __device__ __forceinline__ void radix_pass(const unsigned (&uu)[128], int nreg, unsigned* hist, int lane, unsigned& prefix, int& need) {
;     ...
;     for (int g = 0; g < 8; ++g) {
;         if (g * 16 < nreg) {
; #pragma unroll
;             for (int r = g * 16; r < g * 16 + 16; ++r) {
;                 const unsigned u = uu[r];
;                 const bool match = FIRST ? true : ((u >> (SHIFT + NBITS)) == prefix);
;                 if (match) __hip_atomic_fetch_add(hist + ((u >> SHIFT) & (NBINS - 1)), 1u, __ATOMIC_RELAXED, __HIP_MEMORY_SCOPE_WORKGROUP);
;             }
.LBB0_714:
	v_lshrrev_b32_e32 v129, 10, v82
	v_cmpx_eq_u32_e32 vcc, s55, v129
	v_and_b32_e32 v129, 0x3ff, v82
	v_lshl_add_u32 v129, v129, 2, s97
	ds_add_u32 v129, v176 offset:41984
	s_mov_b64 exec, -1
	v_lshrrev_b32_e32 v129, 10, v81
	v_cmpx_eq_u32_e32 vcc, s55, v129
	v_and_b32_e32 v129, 0x3ff, v81
	v_lshl_add_u32 v129, v129, 2, s97
	ds_add_u32 v129, v176 offset:41984
	s_mov_b64 exec, -1
	v_lshrrev_b32_e32 v129, 10, v80
	v_cmpx_eq_u32_e32 vcc, s55, v129
	v_and_b32_e32 v129, 0x3ff, v80
	v_lshl_add_u32 v129, v129, 2, s97
	ds_add_u32 v129, v176 offset:41984
	s_mov_b64 exec, -1
	v_lshrrev_b32_e32 v129, 10, v78
	v_cmpx_eq_u32_e32 vcc, s55, v129
	v_and_b32_e32 v129, 0x3ff, v78
	v_lshl_add_u32 v129, v129, 2, s97
	ds_add_u32 v129, v176 offset:41984
	s_mov_b64 exec, -1
	v_lshrrev_b32_e32 v129, 10, v77
	v_cmpx_eq_u32_e32 vcc, s55, v129
	v_and_b32_e32 v129, 0x3ff, v77
	v_lshl_add_u32 v129, v129, 2, s97
	ds_add_u32 v129, v176 offset:41984
	s_mov_b64 exec, -1
	v_lshrrev_b32_e32 v129, 10, v76
	v_cmpx_eq_u32_e32 vcc, s55, v129
	v_and_b32_e32 v129, 0x3ff, v76
	v_lshl_add_u32 v129, v129, 2, s97
	ds_add_u32 v129, v176 offset:41984
	s_mov_b64 exec, -1
	v_lshrrev_b32_e32 v129, 10, v75
	v_cmpx_eq_u32_e32 vcc, s55, v129
	v_and_b32_e32 v129, 0x3ff, v75
	v_lshl_add_u32 v129, v129, 2, s97
	ds_add_u32 v129, v176 offset:41984
	s_mov_b64 exec, -1
	v_lshrrev_b32_e32 v129, 10, v74
	v_cmpx_eq_u32_e32 vcc, s55, v129
	v_and_b32_e32 v129, 0x3ff, v74
	v_lshl_add_u32 v129, v129, 2, s97
	ds_add_u32 v129, v176 offset:41984
	s_mov_b64 exec, -1
	v_lshrrev_b32_e32 v129, 10, v73
	v_cmpx_eq_u32_e32 vcc, s55, v129
	v_and_b32_e32 v129, 0x3ff, v73
	v_lshl_add_u32 v129, v129, 2, s97
	ds_add_u32 v129, v176 offset:41984
	s_mov_b64 exec, -1
	v_lshrrev_b32_e32 v129, 10, v72
	v_cmpx_eq_u32_e32 vcc, s55, v129
	v_and_b32_e32 v129, 0x3ff, v72
	v_lshl_add_u32 v129, v129, 2, s97
	ds_add_u32 v129, v176 offset:41984
	s_mov_b64 exec, -1
	v_lshrrev_b32_e32 v129, 10, v71
	v_cmpx_eq_u32_e32 vcc, s55, v129
	v_and_b32_e32 v129, 0x3ff, v71
	v_lshl_add_u32 v129, v129, 2, s97
	ds_add_u32 v129, v176 offset:41984
	s_mov_b64 exec, -1
	v_lshrrev_b32_e32 v129, 10, v70
	v_cmpx_eq_u32_e32 vcc, s55, v129
	v_and_b32_e32 v129, 0x3ff, v70
	v_lshl_add_u32 v129, v129, 2, s97
	ds_add_u32 v129, v176 offset:41984
	s_mov_b64 exec, -1
	v_lshrrev_b32_e32 v129, 10, v69
	v_cmpx_eq_u32_e32 vcc, s55, v129
	v_and_b32_e32 v129, 0x3ff, v69
	v_lshl_add_u32 v129, v129, 2, s97
	ds_add_u32 v129, v176 offset:41984
	s_mov_b64 exec, -1
	v_lshrrev_b32_e32 v129, 10, v68
	v_cmpx_eq_u32_e32 vcc, s55, v129
	v_and_b32_e32 v129, 0x3ff, v68
	v_lshl_add_u32 v129, v129, 2, s97
	ds_add_u32 v129, v176 offset:41984
	s_mov_b64 exec, -1
	v_lshrrev_b32_e32 v129, 10, v67
	v_cmpx_eq_u32_e32 vcc, s55, v129
	v_and_b32_e32 v129, 0x3ff, v67
	v_lshl_add_u32 v129, v129, 2, s97
	ds_add_u32 v129, v176 offset:41984
	s_mov_b64 exec, -1
	v_lshrrev_b32_e32 v129, 10, v65
	v_cmpx_eq_u32_e32 vcc, s55, v129
	v_and_b32_e32 v129, 0x3ff, v65
	v_lshl_add_u32 v129, v129, 2, s97
	ds_add_u32 v129, v176 offset:41984
	s_mov_b64 exec, -1
	s_and_b64 vcc, exec, s[30:31]
	s_cbranch_vccnz .LBB0_644
.LBB0_747:
	v_lshrrev_b32_e32 v129, 10, v66
	v_cmpx_eq_u32_e32 vcc, s55, v129
	v_and_b32_e32 v129, 0x3ff, v66
	v_lshl_add_u32 v129, v129, 2, s97
	ds_add_u32 v129, v176 offset:41984
	s_mov_b64 exec, -1
	v_lshrrev_b32_e32 v129, 10, v64
	v_cmpx_eq_u32_e32 vcc, s55, v129
	v_and_b32_e32 v129, 0x3ff, v64
	v_lshl_add_u32 v129, v129, 2, s97
	ds_add_u32 v129, v176 offset:41984
	s_mov_b64 exec, -1
	v_lshrrev_b32_e32 v129, 10, v63
	v_cmpx_eq_u32_e32 vcc, s55, v129
	v_and_b32_e32 v129, 0x3ff, v63
	v_lshl_add_u32 v129, v129, 2, s97
	ds_add_u32 v129, v176 offset:41984
	s_mov_b64 exec, -1
	v_lshrrev_b32_e32 v129, 10, v62
	v_cmpx_eq_u32_e32 vcc, s55, v129
	v_and_b32_e32 v129, 0x3ff, v62
	v_lshl_add_u32 v129, v129, 2, s97
	ds_add_u32 v129, v176 offset:41984
	s_mov_b64 exec, -1
	v_lshrrev_b32_e32 v129, 10, v61
	v_cmpx_eq_u32_e32 vcc, s55, v129
	v_and_b32_e32 v129, 0x3ff, v61
	v_lshl_add_u32 v129, v129, 2, s97
	ds_add_u32 v129, v176 offset:41984
	s_mov_b64 exec, -1
	v_lshrrev_b32_e32 v129, 10, v60
	v_cmpx_eq_u32_e32 vcc, s55, v129
	v_and_b32_e32 v129, 0x3ff, v60
	v_lshl_add_u32 v129, v129, 2, s97
	ds_add_u32 v129, v176 offset:41984
	s_mov_b64 exec, -1
	v_lshrrev_b32_e32 v129, 10, v59
	v_cmpx_eq_u32_e32 vcc, s55, v129
	v_and_b32_e32 v129, 0x3ff, v59
	v_lshl_add_u32 v129, v129, 2, s97
	ds_add_u32 v129, v176 offset:41984
	s_mov_b64 exec, -1
	v_lshrrev_b32_e32 v129, 10, v58
	v_cmpx_eq_u32_e32 vcc, s55, v129
	v_and_b32_e32 v129, 0x3ff, v58
	v_lshl_add_u32 v129, v129, 2, s97
	ds_add_u32 v129, v176 offset:41984
	s_mov_b64 exec, -1
	v_lshrrev_b32_e32 v129, 10, v57
	v_cmpx_eq_u32_e32 vcc, s55, v129
	v_and_b32_e32 v129, 0x3ff, v57
	v_lshl_add_u32 v129, v129, 2, s97
	ds_add_u32 v129, v176 offset:41984
	s_mov_b64 exec, -1
	v_lshrrev_b32_e32 v129, 10, v56
	v_cmpx_eq_u32_e32 vcc, s55, v129
	v_and_b32_e32 v129, 0x3ff, v56
	v_lshl_add_u32 v129, v129, 2, s97
	ds_add_u32 v129, v176 offset:41984
	s_mov_b64 exec, -1
	v_lshrrev_b32_e32 v129, 10, v55
	v_cmpx_eq_u32_e32 vcc, s55, v129
	v_and_b32_e32 v129, 0x3ff, v55
	v_lshl_add_u32 v129, v129, 2, s97
	ds_add_u32 v129, v176 offset:41984
	s_mov_b64 exec, -1
	v_lshrrev_b32_e32 v129, 10, v54
	v_cmpx_eq_u32_e32 vcc, s55, v129
	v_and_b32_e32 v129, 0x3ff, v54
	v_lshl_add_u32 v129, v129, 2, s97
	ds_add_u32 v129, v176 offset:41984
	s_mov_b64 exec, -1
	v_lshrrev_b32_e32 v129, 10, v53
	v_cmpx_eq_u32_e32 vcc, s55, v129
	v_and_b32_e32 v129, 0x3ff, v53
	v_lshl_add_u32 v129, v129, 2, s97
	ds_add_u32 v129, v176 offset:41984
	s_mov_b64 exec, -1
	v_lshrrev_b32_e32 v129, 10, v52
	v_cmpx_eq_u32_e32 vcc, s55, v129
	v_and_b32_e32 v129, 0x3ff, v52
	v_lshl_add_u32 v129, v129, 2, s97
	ds_add_u32 v129, v176 offset:41984
	s_mov_b64 exec, -1
	v_lshrrev_b32_e32 v129, 10, v51
	v_cmpx_eq_u32_e32 vcc, s55, v129
	v_and_b32_e32 v129, 0x3ff, v51
	v_lshl_add_u32 v129, v129, 2, s97
	ds_add_u32 v129, v176 offset:41984
	s_mov_b64 exec, -1
	v_lshrrev_b32_e32 v129, 10, v47
	v_cmpx_eq_u32_e32 vcc, s55, v129
	v_and_b32_e32 v129, 0x3ff, v47
	v_lshl_add_u32 v129, v129, 2, s97
	ds_add_u32 v129, v176 offset:41984
	s_mov_b64 exec, -1
	s_and_b64 vcc, exec, s[34:35]
	s_cbranch_vccnz .LBB0_645
; template <int SHIFT, int NBITS, bool FIRST>
; __device__ __forceinline__ void radix_pass(const unsigned (&uu)[128], int nreg, unsigned* hist, int lane, unsigned& prefix, int& need) {
;     ...
;     for (int g = 0; g < 8; ++g) {
;         if (g * 16 < nreg) {
; #pragma unroll
;             for (int r = g * 16; r < g * 16 + 16; ++r) {
;                 const unsigned u = uu[r];
;                 const bool match = FIRST ? true : ((u >> (SHIFT + NBITS)) == prefix);
;                 if (match) __hip_atomic_fetch_add(hist + ((u >> SHIFT) & (NBINS - 1)), 1u, __ATOMIC_RELAXED, __HIP_MEMORY_SCOPE_WORKGROUP);
;             }
.LBB0_780:
	v_lshrrev_b32_e32 v129, 10, v50
	v_cmpx_eq_u32_e32 vcc, s55, v129
	v_and_b32_e32 v129, 0x3ff, v50
	v_lshl_add_u32 v129, v129, 2, s97
	ds_add_u32 v129, v176 offset:41984
	s_mov_b64 exec, -1
	v_lshrrev_b32_e32 v129, 10, v49
	v_cmpx_eq_u32_e32 vcc, s55, v129
	v_and_b32_e32 v129, 0x3ff, v49
	v_lshl_add_u32 v129, v129, 2, s97
	ds_add_u32 v129, v176 offset:41984
	s_mov_b64 exec, -1
	v_lshrrev_b32_e32 v129, 10, v48
	v_cmpx_eq_u32_e32 vcc, s55, v129
	v_and_b32_e32 v129, 0x3ff, v48
	v_lshl_add_u32 v129, v129, 2, s97
	ds_add_u32 v129, v176 offset:41984
	s_mov_b64 exec, -1
	v_lshrrev_b32_e32 v129, 10, v46
	v_cmpx_eq_u32_e32 vcc, s55, v129
	v_and_b32_e32 v129, 0x3ff, v46
	v_lshl_add_u32 v129, v129, 2, s97
	ds_add_u32 v129, v176 offset:41984
	s_mov_b64 exec, -1
	v_lshrrev_b32_e32 v129, 10, v45
	v_cmpx_eq_u32_e32 vcc, s55, v129
	v_and_b32_e32 v129, 0x3ff, v45
	v_lshl_add_u32 v129, v129, 2, s97
	ds_add_u32 v129, v176 offset:41984
	s_mov_b64 exec, -1
	v_lshrrev_b32_e32 v129, 10, v44
	v_cmpx_eq_u32_e32 vcc, s55, v129
	v_and_b32_e32 v129, 0x3ff, v44
	v_lshl_add_u32 v129, v129, 2, s97
	ds_add_u32 v129, v176 offset:41984
	s_mov_b64 exec, -1
	v_lshrrev_b32_e32 v129, 10, v43
	v_cmpx_eq_u32_e32 vcc, s55, v129
	v_and_b32_e32 v129, 0x3ff, v43
	v_lshl_add_u32 v129, v129, 2, s97
	ds_add_u32 v129, v176 offset:41984
	s_mov_b64 exec, -1
	v_lshrrev_b32_e32 v129, 10, v42
	v_cmpx_eq_u32_e32 vcc, s55, v129
	v_and_b32_e32 v129, 0x3ff, v42
	v_lshl_add_u32 v129, v129, 2, s97
	ds_add_u32 v129, v176 offset:41984
	s_mov_b64 exec, -1
	v_lshrrev_b32_e32 v129, 10, v41
	v_cmpx_eq_u32_e32 vcc, s55, v129
	v_and_b32_e32 v129, 0x3ff, v41
	v_lshl_add_u32 v129, v129, 2, s97
	ds_add_u32 v129, v176 offset:41984
	s_mov_b64 exec, -1
	v_lshrrev_b32_e32 v129, 10, v40
	v_cmpx_eq_u32_e32 vcc, s55, v129
	v_and_b32_e32 v129, 0x3ff, v40
	v_lshl_add_u32 v129, v129, 2, s97
	ds_add_u32 v129, v176 offset:41984
	s_mov_b64 exec, -1
	v_lshrrev_b32_e32 v129, 10, v39
	v_cmpx_eq_u32_e32 vcc, s55, v129
	v_and_b32_e32 v129, 0x3ff, v39
	v_lshl_add_u32 v129, v129, 2, s97
	ds_add_u32 v129, v176 offset:41984
	s_mov_b64 exec, -1
	v_lshrrev_b32_e32 v129, 10, v38
	v_cmpx_eq_u32_e32 vcc, s55, v129
	v_and_b32_e32 v129, 0x3ff, v38
	v_lshl_add_u32 v129, v129, 2, s97
	ds_add_u32 v129, v176 offset:41984
	s_mov_b64 exec, -1
	v_lshrrev_b32_e32 v129, 10, v37
	v_cmpx_eq_u32_e32 vcc, s55, v129
	v_and_b32_e32 v129, 0x3ff, v37
	v_lshl_add_u32 v129, v129, 2, s97
	ds_add_u32 v129, v176 offset:41984
	s_mov_b64 exec, -1
	v_lshrrev_b32_e32 v129, 10, v36
	v_cmpx_eq_u32_e32 vcc, s55, v129
	v_and_b32_e32 v129, 0x3ff, v36
	v_lshl_add_u32 v129, v129, 2, s97
	ds_add_u32 v129, v176 offset:41984
	s_mov_b64 exec, -1
	v_lshrrev_b32_e32 v129, 10, v35
	v_cmpx_eq_u32_e32 vcc, s55, v129
	v_and_b32_e32 v129, 0x3ff, v35
	v_lshl_add_u32 v129, v129, 2, s97
	ds_add_u32 v129, v176 offset:41984
	s_mov_b64 exec, -1
	v_lshrrev_b32_e32 v129, 10, v33
	v_cmpx_eq_u32_e32 vcc, s55, v129
	v_and_b32_e32 v129, 0x3ff, v33
	v_lshl_add_u32 v129, v129, 2, s97
	ds_add_u32 v129, v176 offset:41984
	s_mov_b64 exec, -1
	s_and_b64 vcc, exec, s[36:37]
	s_cbranch_vccnz .LBB0_646
; template <int SHIFT, int NBITS, bool FIRST>
; __device__ __forceinline__ void radix_pass(const unsigned (&uu)[128], int nreg, unsigned* hist, int lane, unsigned& prefix, int& need) {
;     ...
;     for (int g = 0; g < 8; ++g) {
;         if (g * 16 < nreg) {
; #pragma unroll
;             for (int r = g * 16; r < g * 16 + 16; ++r) {
;                 const unsigned u = uu[r];
;                 const bool match = FIRST ? true : ((u >> (SHIFT + NBITS)) == prefix);
;                 if (match) __hip_atomic_fetch_add(hist + ((u >> SHIFT) & (NBINS - 1)), 1u, __ATOMIC_RELAXED, __HIP_MEMORY_SCOPE_WORKGROUP);
;             }
.LBB0_813:
	v_lshrrev_b32_e32 v129, 10, v34
	v_cmpx_eq_u32_e32 vcc, s55, v129
	v_and_b32_e32 v129, 0x3ff, v34
	v_lshl_add_u32 v129, v129, 2, s97
	ds_add_u32 v129, v176 offset:41984
	s_mov_b64 exec, -1
	v_lshrrev_b32_e32 v129, 10, v32
	v_cmpx_eq_u32_e32 vcc, s55, v129
	v_and_b32_e32 v129, 0x3ff, v32
	v_lshl_add_u32 v129, v129, 2, s97
	ds_add_u32 v129, v176 offset:41984
	s_mov_b64 exec, -1
	v_lshrrev_b32_e32 v129, 10, v31
	v_cmpx_eq_u32_e32 vcc, s55, v129
	v_and_b32_e32 v129, 0x3ff, v31
	v_lshl_add_u32 v129, v129, 2, s97
	ds_add_u32 v129, v176 offset:41984
	s_mov_b64 exec, -1
	v_lshrrev_b32_e32 v129, 10, v30
	v_cmpx_eq_u32_e32 vcc, s55, v129
	v_and_b32_e32 v129, 0x3ff, v30
	v_lshl_add_u32 v129, v129, 2, s97
	ds_add_u32 v129, v176 offset:41984
	s_mov_b64 exec, -1
	v_lshrrev_b32_e32 v129, 10, v29
	v_cmpx_eq_u32_e32 vcc, s55, v129
	v_and_b32_e32 v129, 0x3ff, v29
	v_lshl_add_u32 v129, v129, 2, s97
	ds_add_u32 v129, v176 offset:41984
	s_mov_b64 exec, -1
	v_lshrrev_b32_e32 v129, 10, v28
	v_cmpx_eq_u32_e32 vcc, s55, v129
	v_and_b32_e32 v129, 0x3ff, v28
	v_lshl_add_u32 v129, v129, 2, s97
	ds_add_u32 v129, v176 offset:41984
	s_mov_b64 exec, -1
	v_lshrrev_b32_e32 v129, 10, v27
	v_cmpx_eq_u32_e32 vcc, s55, v129
	v_and_b32_e32 v129, 0x3ff, v27
	v_lshl_add_u32 v129, v129, 2, s97
	ds_add_u32 v129, v176 offset:41984
	s_mov_b64 exec, -1
	v_lshrrev_b32_e32 v129, 10, v26
	v_cmpx_eq_u32_e32 vcc, s55, v129
	v_and_b32_e32 v129, 0x3ff, v26
	v_lshl_add_u32 v129, v129, 2, s97
	ds_add_u32 v129, v176 offset:41984
	s_mov_b64 exec, -1
	v_lshrrev_b32_e32 v129, 10, v25
	v_cmpx_eq_u32_e32 vcc, s55, v129
	v_and_b32_e32 v129, 0x3ff, v25
	v_lshl_add_u32 v129, v129, 2, s97
	ds_add_u32 v129, v176 offset:41984
	s_mov_b64 exec, -1
	v_lshrrev_b32_e32 v129, 10, v24
	v_cmpx_eq_u32_e32 vcc, s55, v129
	v_and_b32_e32 v129, 0x3ff, v24
	v_lshl_add_u32 v129, v129, 2, s97
	ds_add_u32 v129, v176 offset:41984
	s_mov_b64 exec, -1
	v_lshrrev_b32_e32 v129, 10, v23
	v_cmpx_eq_u32_e32 vcc, s55, v129
	v_and_b32_e32 v129, 0x3ff, v23
	v_lshl_add_u32 v129, v129, 2, s97
	ds_add_u32 v129, v176 offset:41984
	s_mov_b64 exec, -1
	v_lshrrev_b32_e32 v129, 10, v22
	v_cmpx_eq_u32_e32 vcc, s55, v129
	v_and_b32_e32 v129, 0x3ff, v22
	v_lshl_add_u32 v129, v129, 2, s97
	ds_add_u32 v129, v176 offset:41984
	s_mov_b64 exec, -1
	v_lshrrev_b32_e32 v129, 10, v21
	v_cmpx_eq_u32_e32 vcc, s55, v129
	v_and_b32_e32 v129, 0x3ff, v21
	v_lshl_add_u32 v129, v129, 2, s97
	ds_add_u32 v129, v176 offset:41984
	s_mov_b64 exec, -1
	v_lshrrev_b32_e32 v129, 10, v20
	v_cmpx_eq_u32_e32 vcc, s55, v129
	v_and_b32_e32 v129, 0x3ff, v20
	v_lshl_add_u32 v129, v129, 2, s97
	ds_add_u32 v129, v176 offset:41984
	s_mov_b64 exec, -1
	v_lshrrev_b32_e32 v129, 10, v19
	v_cmpx_eq_u32_e32 vcc, s55, v129
	v_and_b32_e32 v129, 0x3ff, v19
	v_lshl_add_u32 v129, v129, 2, s97
	ds_add_u32 v129, v176 offset:41984
	s_mov_b64 exec, -1
	v_lshrrev_b32_e32 v129, 10, v15
	v_cmpx_eq_u32_e32 vcc, s55, v129
	v_and_b32_e32 v129, 0x3ff, v15
	v_lshl_add_u32 v129, v129, 2, s97
	ds_add_u32 v129, v176 offset:41984
	s_mov_b64 exec, -1
	s_and_b64 vcc, exec, s[38:39]
	s_cbranch_vccnz .LBB0_879
.LBB0_846:
	v_lshrrev_b32_e32 v129, 10, v18
	v_cmpx_eq_u32_e32 vcc, s55, v129
	v_and_b32_e32 v129, 0x3ff, v18
	v_lshl_add_u32 v129, v129, 2, s97
	ds_add_u32 v129, v176 offset:41984
	s_mov_b64 exec, -1
	v_lshrrev_b32_e32 v129, 10, v17
	v_cmpx_eq_u32_e32 vcc, s55, v129
	v_and_b32_e32 v129, 0x3ff, v17
	v_lshl_add_u32 v129, v129, 2, s97
	ds_add_u32 v129, v176 offset:41984
	s_mov_b64 exec, -1
	v_lshrrev_b32_e32 v129, 10, v16
	v_cmpx_eq_u32_e32 vcc, s55, v129
	v_and_b32_e32 v129, 0x3ff, v16
	v_lshl_add_u32 v129, v129, 2, s97
	ds_add_u32 v129, v176 offset:41984
	s_mov_b64 exec, -1
	v_lshrrev_b32_e32 v129, 10, v14
	v_cmpx_eq_u32_e32 vcc, s55, v129
	v_and_b32_e32 v129, 0x3ff, v14
	v_lshl_add_u32 v129, v129, 2, s97
	ds_add_u32 v129, v176 offset:41984
	s_mov_b64 exec, -1
	v_lshrrev_b32_e32 v129, 10, v13
	v_cmpx_eq_u32_e32 vcc, s55, v129
	v_and_b32_e32 v129, 0x3ff, v13
	v_lshl_add_u32 v129, v129, 2, s97
	ds_add_u32 v129, v176 offset:41984
	s_mov_b64 exec, -1
	v_lshrrev_b32_e32 v129, 10, v12
	v_cmpx_eq_u32_e32 vcc, s55, v129
	v_and_b32_e32 v129, 0x3ff, v12
	v_lshl_add_u32 v129, v129, 2, s97
	ds_add_u32 v129, v176 offset:41984
	s_mov_b64 exec, -1
	v_lshrrev_b32_e32 v129, 10, v11
	v_cmpx_eq_u32_e32 vcc, s55, v129
	v_and_b32_e32 v129, 0x3ff, v11
	v_lshl_add_u32 v129, v129, 2, s97
	ds_add_u32 v129, v176 offset:41984
	s_mov_b64 exec, -1
	v_lshrrev_b32_e32 v129, 10, v10
	v_cmpx_eq_u32_e32 vcc, s55, v129
	v_and_b32_e32 v129, 0x3ff, v10
	v_lshl_add_u32 v129, v129, 2, s97
	ds_add_u32 v129, v176 offset:41984
	s_mov_b64 exec, -1
	v_lshrrev_b32_e32 v129, 10, v9
	v_cmpx_eq_u32_e32 vcc, s55, v129
	v_and_b32_e32 v129, 0x3ff, v9
	v_lshl_add_u32 v129, v129, 2, s97
	ds_add_u32 v129, v176 offset:41984
	s_mov_b64 exec, -1
	v_lshrrev_b32_e32 v129, 10, v8
	v_cmpx_eq_u32_e32 vcc, s55, v129
	v_and_b32_e32 v129, 0x3ff, v8
	v_lshl_add_u32 v129, v129, 2, s97
	ds_add_u32 v129, v176 offset:41984
	s_mov_b64 exec, -1
	v_lshrrev_b32_e32 v129, 10, v7
	v_cmpx_eq_u32_e32 vcc, s55, v129
	v_and_b32_e32 v129, 0x3ff, v7
	v_lshl_add_u32 v129, v129, 2, s97
	ds_add_u32 v129, v176 offset:41984
	s_mov_b64 exec, -1
	v_lshrrev_b32_e32 v129, 10, v6
	v_cmpx_eq_u32_e32 vcc, s55, v129
	v_and_b32_e32 v129, 0x3ff, v6
	v_lshl_add_u32 v129, v129, 2, s97
	ds_add_u32 v129, v176 offset:41984
	s_mov_b64 exec, -1
	v_lshrrev_b32_e32 v129, 10, v5
	v_cmpx_eq_u32_e32 vcc, s55, v129
	v_and_b32_e32 v129, 0x3ff, v5
	v_lshl_add_u32 v129, v129, 2, s97
	ds_add_u32 v129, v176 offset:41984
	s_mov_b64 exec, -1
	v_lshrrev_b32_e32 v129, 10, v4
	v_cmpx_eq_u32_e32 vcc, s55, v129
	v_and_b32_e32 v129, 0x3ff, v4
	v_lshl_add_u32 v129, v129, 2, s97
	ds_add_u32 v129, v176 offset:41984
	s_mov_b64 exec, -1
	v_lshrrev_b32_e32 v129, 10, v3
	v_cmpx_eq_u32_e32 vcc, s55, v129
	v_and_b32_e32 v129, 0x3ff, v3
	v_lshl_add_u32 v129, v129, 2, s97
	ds_add_u32 v129, v176 offset:41984
	s_mov_b64 exec, -1
	v_lshrrev_b32_e32 v129, 10, v2
	v_cmpx_eq_u32_e32 vcc, s55, v129
	v_and_b32_e32 v129, 0x3ff, v2
	v_lshl_add_u32 v129, v129, 2, s97
	ds_add_u32 v129, v176 offset:41984
	s_mov_b64 exec, -1
